# adds hand-written epilogues for W_in (P3) and the two residual GEMMs (P2,P6): prefetched row sums, load ring with counted vmcnt, batched reductions
# speedup vs baseline: 1.0133x; 1.0049x over previous
.LBB0_266:
	v_readlane_b32 s52, v253, 7
	v_readlane_b32 s53, v253, 8
	v_readlane_b32 s54, v253, 9
	v_readlane_b32 s55, v253, 10
	v_readlane_b32 s56, v253, 11
	v_readlane_b32 s57, v253, 12
	v_readlane_b32 s58, v253, 13
	v_readlane_b32 s59, v253, 14
	v_readlane_b32 s60, v253, 15
	v_readlane_b32 s61, v253, 16
	v_readlane_b32 s62, v253, 17
	v_readlane_b32 s63, v253, 18
	v_readlane_b32 s64, v253, 19
	v_readlane_b32 s65, v253, 20
	v_readlane_b32 s66, v253, 21
	v_readlane_b32 s67, v253, 22
	v_lshl_add_u32 v245, s42, 8, v144
	v_lshl_or_b32 v240, s43, 8, v146
	v_lshl_add_u32 v239, v245, 11, v240
	v_lshlrev_b32_e32 v238, 2, v239
	v_lshlrev_b32_e32 v239, 1, v239
	v_lshlrev_b32_e32 v241, 2, v245
	v_mov_b32_e32 v240, v238
	global_load_dwordx4 v[140:143], v240, s[52:53]
	global_load_dwordx4 v[150:153], v240, s[52:53] offset:64
	global_load_dwordx4 v[154:157], v240, s[52:53] offset:512
	global_load_dwordx4 v[158:161], v240, s[52:53] offset:576
	v_add_u32_e32 v240, 0x20000, v238
	global_load_dwordx4 v[162:165], v240, s[52:53]
	global_load_dwordx4 v[166:169], v240, s[52:53] offset:64
	global_load_dwordx4 v[170:173], v240, s[52:53] offset:512
	global_load_dwordx4 v[174:177], v240, s[52:53] offset:576
	v_add_u32_e32 v240, 0x40000, v238
	global_load_dwordx4 v[180:183], v240, s[52:53]
	global_load_dwordx4 v[184:187], v240, s[52:53] offset:64
	global_load_dwordx4 v[192:195], v240, s[52:53] offset:512
	global_load_dwordx4 v[196:199], v240, s[52:53] offset:576
	v_add_u32_e32 v240, 0x60000, v238
	global_load_dwordx4 v[200:203], v240, s[52:53]
	global_load_dwordx4 v[204:207], v240, s[52:53] offset:64
	global_load_dwordx4 v[208:211], v240, s[52:53] offset:512
	global_load_dwordx4 v[212:215], v240, s[52:53] offset:576
	v_add_u32_e32 v240, 0x100000, v238
	global_load_dwordx4 v[216:219], v240, s[52:53]
	global_load_dwordx4 v[220:223], v240, s[52:53] offset:64
	global_load_dwordx4 v[224:227], v240, s[52:53] offset:512
	global_load_dwordx4 v[228:231], v240, s[52:53] offset:576
	v_mbcnt_lo_u32_b32 v242, -1, 0
	v_mbcnt_hi_u32_b32 v242, -1, v242
	v_xor_b32_e32 v243, 16, v242
	v_xor_b32_e32 v244, 32, v242
	v_lshlrev_b32_e32 v243, 2, v243
	v_lshlrev_b32_e32 v244, 2, v244
	s_waitcnt vmcnt(16)
	v_pk_fma_f32 v[124:125], v[124:125], 0.5, v[140:141] op_sel_hi:[1,0,1]
	v_pk_fma_f32 v[126:127], v[126:127], 0.5, v[142:143] op_sel_hi:[1,0,1]
	v_pk_fma_f32 v[120:121], v[120:121], 0.5, v[150:151] op_sel_hi:[1,0,1]
	v_pk_fma_f32 v[122:123], v[122:123], 0.5, v[152:153] op_sel_hi:[1,0,1]
	v_pk_fma_f32 v[116:117], v[116:117], 0.5, v[154:155] op_sel_hi:[1,0,1]
	v_pk_fma_f32 v[118:119], v[118:119], 0.5, v[156:157] op_sel_hi:[1,0,1]
	v_pk_fma_f32 v[112:113], v[112:113], 0.5, v[158:159] op_sel_hi:[1,0,1]
	v_pk_fma_f32 v[114:115], v[114:115], 0.5, v[160:161] op_sel_hi:[1,0,1]
	v_mul_f32_e32 v140, v125, v125
	v_mul_f32_e32 v150, v121, v121
	v_mul_f32_e32 v154, v117, v117
	v_mul_f32_e32 v158, v113, v113
	v_mul_f32_e32 v141, v127, v127
	v_mul_f32_e32 v151, v123, v123
	v_mul_f32_e32 v155, v119, v119
	v_mul_f32_e32 v159, v115, v115
	v_fmac_f32_e32 v140, v124, v124
	v_fmac_f32_e32 v150, v120, v120
	v_fmac_f32_e32 v154, v116, v116
	v_fmac_f32_e32 v158, v112, v112
	v_fmac_f32_e32 v141, v126, v126
	v_fmac_f32_e32 v151, v122, v122
	v_fmac_f32_e32 v155, v118, v118
	v_fmac_f32_e32 v159, v114, v114
	v_add_f32_e32 v140, v140, v141
	v_add_f32_e32 v150, v150, v151
	v_add_f32_e32 v154, v154, v155
	v_add_f32_e32 v158, v158, v159
	v_add_f32_e32 v188, v140, v150
	v_cvt_pk_bf16_f32 v124, v124, v125
	v_cvt_pk_bf16_f32 v125, v126, v127
	v_cvt_pk_bf16_f32 v120, v120, v121
	v_cvt_pk_bf16_f32 v121, v122, v123
	v_cvt_pk_bf16_f32 v116, v116, v117
	v_cvt_pk_bf16_f32 v117, v118, v119
	v_cvt_pk_bf16_f32 v112, v112, v113
	v_cvt_pk_bf16_f32 v113, v114, v115
	v_add_f32_e32 v188, v188, v154
	v_add_f32_e32 v188, v188, v158
	v_mov_b32_e32 v240, v239
	global_store_dwordx2 v240, v[124:125], s[18:19]
	global_store_dwordx2 v240, v[120:121], s[18:19] offset:32
	global_store_dwordx2 v240, v[116:117], s[18:19] offset:256
	global_store_dwordx2 v240, v[112:113], s[18:19] offset:288
	v_add_u32_e32 v240, 0x120000, v238
	global_load_dwordx4 v[140:143], v240, s[52:53]
	global_load_dwordx4 v[150:153], v240, s[52:53] offset:64
	global_load_dwordx4 v[154:157], v240, s[52:53] offset:512
	global_load_dwordx4 v[158:161], v240, s[52:53] offset:576
	s_waitcnt vmcnt(20)
	v_pk_fma_f32 v[108:109], v[108:109], 0.5, v[162:163] op_sel_hi:[1,0,1]
	v_pk_fma_f32 v[110:111], v[110:111], 0.5, v[164:165] op_sel_hi:[1,0,1]
	v_pk_fma_f32 v[104:105], v[104:105], 0.5, v[166:167] op_sel_hi:[1,0,1]
	v_pk_fma_f32 v[106:107], v[106:107], 0.5, v[168:169] op_sel_hi:[1,0,1]
	v_pk_fma_f32 v[100:101], v[100:101], 0.5, v[170:171] op_sel_hi:[1,0,1]
	v_pk_fma_f32 v[102:103], v[102:103], 0.5, v[172:173] op_sel_hi:[1,0,1]
	v_pk_fma_f32 v[96:97], v[96:97], 0.5, v[174:175] op_sel_hi:[1,0,1]
	v_pk_fma_f32 v[98:99], v[98:99], 0.5, v[176:177] op_sel_hi:[1,0,1]
	v_mul_f32_e32 v162, v109, v109
	v_mul_f32_e32 v166, v105, v105
	v_mul_f32_e32 v170, v101, v101
	v_mul_f32_e32 v174, v97, v97
	v_mul_f32_e32 v163, v111, v111
	v_mul_f32_e32 v167, v107, v107
	v_mul_f32_e32 v171, v103, v103
	v_mul_f32_e32 v175, v99, v99
	v_fmac_f32_e32 v162, v108, v108
	v_fmac_f32_e32 v166, v104, v104
	v_fmac_f32_e32 v170, v100, v100
	v_fmac_f32_e32 v174, v96, v96
	v_fmac_f32_e32 v163, v110, v110
	v_fmac_f32_e32 v167, v106, v106
	v_fmac_f32_e32 v171, v102, v102
	v_fmac_f32_e32 v175, v98, v98
	v_add_f32_e32 v162, v162, v163
	v_add_f32_e32 v166, v166, v167
	v_add_f32_e32 v170, v170, v171
	v_add_f32_e32 v174, v174, v175
	v_add_f32_e32 v189, v162, v166
	v_cvt_pk_bf16_f32 v108, v108, v109
	v_cvt_pk_bf16_f32 v109, v110, v111
	v_cvt_pk_bf16_f32 v104, v104, v105
	v_cvt_pk_bf16_f32 v105, v106, v107
	v_cvt_pk_bf16_f32 v100, v100, v101
	v_cvt_pk_bf16_f32 v101, v102, v103
	v_cvt_pk_bf16_f32 v96, v96, v97
	v_cvt_pk_bf16_f32 v97, v98, v99
	v_add_f32_e32 v189, v189, v170
	v_add_f32_e32 v189, v189, v174
	v_add_u32_e32 v240, 0x10000, v239
	global_store_dwordx2 v240, v[108:109], s[18:19]
	global_store_dwordx2 v240, v[104:105], s[18:19] offset:32
	global_store_dwordx2 v240, v[100:101], s[18:19] offset:256
	global_store_dwordx2 v240, v[96:97], s[18:19] offset:288
	v_add_u32_e32 v240, 0x140000, v238
	global_load_dwordx4 v[162:165], v240, s[52:53]
	global_load_dwordx4 v[166:169], v240, s[52:53] offset:64
	global_load_dwordx4 v[170:173], v240, s[52:53] offset:512
	global_load_dwordx4 v[174:177], v240, s[52:53] offset:576
	s_waitcnt vmcnt(24)
	v_pk_fma_f32 v[92:93], v[92:93], 0.5, v[180:181] op_sel_hi:[1,0,1]
	v_pk_fma_f32 v[94:95], v[94:95], 0.5, v[182:183] op_sel_hi:[1,0,1]
	v_pk_fma_f32 v[88:89], v[88:89], 0.5, v[184:185] op_sel_hi:[1,0,1]
	v_pk_fma_f32 v[90:91], v[90:91], 0.5, v[186:187] op_sel_hi:[1,0,1]
	v_pk_fma_f32 v[84:85], v[84:85], 0.5, v[192:193] op_sel_hi:[1,0,1]
	v_pk_fma_f32 v[86:87], v[86:87], 0.5, v[194:195] op_sel_hi:[1,0,1]
	v_pk_fma_f32 v[80:81], v[80:81], 0.5, v[196:197] op_sel_hi:[1,0,1]
	v_pk_fma_f32 v[82:83], v[82:83], 0.5, v[198:199] op_sel_hi:[1,0,1]
	v_mul_f32_e32 v180, v93, v93
	v_mul_f32_e32 v184, v89, v89
	v_mul_f32_e32 v192, v85, v85
	v_mul_f32_e32 v196, v81, v81
	v_mul_f32_e32 v181, v95, v95
	v_mul_f32_e32 v185, v91, v91
	v_mul_f32_e32 v193, v87, v87
	v_mul_f32_e32 v197, v83, v83
	v_fmac_f32_e32 v180, v92, v92
	v_fmac_f32_e32 v184, v88, v88
	v_fmac_f32_e32 v192, v84, v84
	v_fmac_f32_e32 v196, v80, v80
	v_fmac_f32_e32 v181, v94, v94
	v_fmac_f32_e32 v185, v90, v90
	v_fmac_f32_e32 v193, v86, v86
	v_fmac_f32_e32 v197, v82, v82
	v_add_f32_e32 v180, v180, v181
	v_add_f32_e32 v184, v184, v185
	v_add_f32_e32 v192, v192, v193
	v_add_f32_e32 v196, v196, v197
	v_add_f32_e32 v232, v180, v184
	v_cvt_pk_bf16_f32 v92, v92, v93
	v_cvt_pk_bf16_f32 v93, v94, v95
	v_cvt_pk_bf16_f32 v88, v88, v89
	v_cvt_pk_bf16_f32 v89, v90, v91
	v_cvt_pk_bf16_f32 v84, v84, v85
	v_cvt_pk_bf16_f32 v85, v86, v87
	v_cvt_pk_bf16_f32 v80, v80, v81
	v_cvt_pk_bf16_f32 v81, v82, v83
	v_add_f32_e32 v232, v232, v192
	v_add_f32_e32 v232, v232, v196
	v_add_u32_e32 v240, 0x20000, v239
	global_store_dwordx2 v240, v[92:93], s[18:19]
	global_store_dwordx2 v240, v[88:89], s[18:19] offset:32
	global_store_dwordx2 v240, v[84:85], s[18:19] offset:256
	global_store_dwordx2 v240, v[80:81], s[18:19] offset:288
	v_add_u32_e32 v240, 0x160000, v238
	global_load_dwordx4 v[180:183], v240, s[52:53]
	global_load_dwordx4 v[184:187], v240, s[52:53] offset:64
	global_load_dwordx4 v[192:195], v240, s[52:53] offset:512
	global_load_dwordx4 v[196:199], v240, s[52:53] offset:576
	s_waitcnt vmcnt(28)
	v_pk_fma_f32 v[76:77], v[76:77], 0.5, v[200:201] op_sel_hi:[1,0,1]
	v_pk_fma_f32 v[78:79], v[78:79], 0.5, v[202:203] op_sel_hi:[1,0,1]
	v_pk_fma_f32 v[72:73], v[72:73], 0.5, v[204:205] op_sel_hi:[1,0,1]
	v_pk_fma_f32 v[74:75], v[74:75], 0.5, v[206:207] op_sel_hi:[1,0,1]
	v_pk_fma_f32 v[68:69], v[68:69], 0.5, v[208:209] op_sel_hi:[1,0,1]
	v_pk_fma_f32 v[70:71], v[70:71], 0.5, v[210:211] op_sel_hi:[1,0,1]
	v_pk_fma_f32 v[64:65], v[64:65], 0.5, v[212:213] op_sel_hi:[1,0,1]
	v_pk_fma_f32 v[66:67], v[66:67], 0.5, v[214:215] op_sel_hi:[1,0,1]
	v_mul_f32_e32 v200, v77, v77
	v_mul_f32_e32 v204, v73, v73
	v_mul_f32_e32 v208, v69, v69
	v_mul_f32_e32 v212, v65, v65
	v_mul_f32_e32 v201, v79, v79
	v_mul_f32_e32 v205, v75, v75
	v_mul_f32_e32 v209, v71, v71
	v_mul_f32_e32 v213, v67, v67
	v_fmac_f32_e32 v200, v76, v76
	v_fmac_f32_e32 v204, v72, v72
	v_fmac_f32_e32 v208, v68, v68
	v_fmac_f32_e32 v212, v64, v64
	v_fmac_f32_e32 v201, v78, v78
	v_fmac_f32_e32 v205, v74, v74
	v_fmac_f32_e32 v209, v70, v70
	v_fmac_f32_e32 v213, v66, v66
	v_add_f32_e32 v200, v200, v201
	v_add_f32_e32 v204, v204, v205
	v_add_f32_e32 v208, v208, v209
	v_add_f32_e32 v212, v212, v213
	v_add_f32_e32 v233, v200, v204
	v_cvt_pk_bf16_f32 v76, v76, v77
	v_cvt_pk_bf16_f32 v77, v78, v79
	v_cvt_pk_bf16_f32 v72, v72, v73
	v_cvt_pk_bf16_f32 v73, v74, v75
	v_cvt_pk_bf16_f32 v68, v68, v69
	v_cvt_pk_bf16_f32 v69, v70, v71
	v_cvt_pk_bf16_f32 v64, v64, v65
	v_cvt_pk_bf16_f32 v65, v66, v67
	v_add_f32_e32 v233, v233, v208
	v_add_f32_e32 v233, v233, v212
	v_add_u32_e32 v240, 0x30000, v239
	global_store_dwordx2 v240, v[76:77], s[18:19]
	global_store_dwordx2 v240, v[72:73], s[18:19] offset:32
	global_store_dwordx2 v240, v[68:69], s[18:19] offset:256
	global_store_dwordx2 v240, v[64:65], s[18:19] offset:288
	s_waitcnt vmcnt(28)
	v_pk_fma_f32 v[60:61], v[60:61], 0.5, v[216:217] op_sel_hi:[1,0,1]
	v_pk_fma_f32 v[62:63], v[62:63], 0.5, v[218:219] op_sel_hi:[1,0,1]
	v_pk_fma_f32 v[56:57], v[56:57], 0.5, v[220:221] op_sel_hi:[1,0,1]
	v_pk_fma_f32 v[58:59], v[58:59], 0.5, v[222:223] op_sel_hi:[1,0,1]
	v_pk_fma_f32 v[52:53], v[52:53], 0.5, v[224:225] op_sel_hi:[1,0,1]
	v_pk_fma_f32 v[54:55], v[54:55], 0.5, v[226:227] op_sel_hi:[1,0,1]
	v_pk_fma_f32 v[48:49], v[48:49], 0.5, v[228:229] op_sel_hi:[1,0,1]
	v_pk_fma_f32 v[50:51], v[50:51], 0.5, v[230:231] op_sel_hi:[1,0,1]
	v_mul_f32_e32 v216, v61, v61
	v_mul_f32_e32 v220, v57, v57
	v_mul_f32_e32 v224, v53, v53
	v_mul_f32_e32 v228, v49, v49
	v_mul_f32_e32 v217, v63, v63
	v_mul_f32_e32 v221, v59, v59
	v_mul_f32_e32 v225, v55, v55
	v_mul_f32_e32 v229, v51, v51
	v_fmac_f32_e32 v216, v60, v60
	v_fmac_f32_e32 v220, v56, v56
	v_fmac_f32_e32 v224, v52, v52
	v_fmac_f32_e32 v228, v48, v48
	v_fmac_f32_e32 v217, v62, v62
	v_fmac_f32_e32 v221, v58, v58
	v_fmac_f32_e32 v225, v54, v54
	v_fmac_f32_e32 v229, v50, v50
	v_add_f32_e32 v216, v216, v217
	v_add_f32_e32 v220, v220, v221
	v_add_f32_e32 v224, v224, v225
	v_add_f32_e32 v228, v228, v229
	v_add_f32_e32 v234, v216, v220
	v_cvt_pk_bf16_f32 v60, v60, v61
	v_cvt_pk_bf16_f32 v61, v62, v63
	v_cvt_pk_bf16_f32 v56, v56, v57
	v_cvt_pk_bf16_f32 v57, v58, v59
	v_cvt_pk_bf16_f32 v52, v52, v53
	v_cvt_pk_bf16_f32 v53, v54, v55
	v_cvt_pk_bf16_f32 v48, v48, v49
	v_cvt_pk_bf16_f32 v49, v50, v51
	v_add_f32_e32 v234, v234, v224
	v_add_f32_e32 v234, v234, v228
	v_add_u32_e32 v240, 0x80000, v239
	global_store_dwordx2 v240, v[60:61], s[18:19]
	global_store_dwordx2 v240, v[56:57], s[18:19] offset:32
	global_store_dwordx2 v240, v[52:53], s[18:19] offset:256
	global_store_dwordx2 v240, v[48:49], s[18:19] offset:288
	s_waitcnt vmcnt(24)
	v_pk_fma_f32 v[44:45], v[44:45], 0.5, v[140:141] op_sel_hi:[1,0,1]
	v_pk_fma_f32 v[46:47], v[46:47], 0.5, v[142:143] op_sel_hi:[1,0,1]
	v_pk_fma_f32 v[40:41], v[40:41], 0.5, v[150:151] op_sel_hi:[1,0,1]
	v_pk_fma_f32 v[42:43], v[42:43], 0.5, v[152:153] op_sel_hi:[1,0,1]
	v_pk_fma_f32 v[36:37], v[36:37], 0.5, v[154:155] op_sel_hi:[1,0,1]
	v_pk_fma_f32 v[38:39], v[38:39], 0.5, v[156:157] op_sel_hi:[1,0,1]
	v_pk_fma_f32 v[32:33], v[32:33], 0.5, v[158:159] op_sel_hi:[1,0,1]
	v_pk_fma_f32 v[34:35], v[34:35], 0.5, v[160:161] op_sel_hi:[1,0,1]
	v_mul_f32_e32 v140, v45, v45
	v_mul_f32_e32 v150, v41, v41
	v_mul_f32_e32 v154, v37, v37
	v_mul_f32_e32 v158, v33, v33
	v_mul_f32_e32 v141, v47, v47
	v_mul_f32_e32 v151, v43, v43
	v_mul_f32_e32 v155, v39, v39
	v_mul_f32_e32 v159, v35, v35
	v_fmac_f32_e32 v140, v44, v44
	v_fmac_f32_e32 v150, v40, v40
	v_fmac_f32_e32 v154, v36, v36
	v_fmac_f32_e32 v158, v32, v32
	v_fmac_f32_e32 v141, v46, v46
	v_fmac_f32_e32 v151, v42, v42
	v_fmac_f32_e32 v155, v38, v38
	v_fmac_f32_e32 v159, v34, v34
	v_add_f32_e32 v140, v140, v141
	v_add_f32_e32 v150, v150, v151
	v_add_f32_e32 v154, v154, v155
	v_add_f32_e32 v158, v158, v159
	v_add_f32_e32 v235, v140, v150
	v_cvt_pk_bf16_f32 v44, v44, v45
	v_cvt_pk_bf16_f32 v45, v46, v47
	v_cvt_pk_bf16_f32 v40, v40, v41
	v_cvt_pk_bf16_f32 v41, v42, v43
	v_cvt_pk_bf16_f32 v36, v36, v37
	v_cvt_pk_bf16_f32 v37, v38, v39
	v_cvt_pk_bf16_f32 v32, v32, v33
	v_cvt_pk_bf16_f32 v33, v34, v35
	v_add_f32_e32 v235, v235, v154
	v_add_f32_e32 v235, v235, v158
	v_add_u32_e32 v240, 0x90000, v239
	global_store_dwordx2 v240, v[44:45], s[18:19]
	global_store_dwordx2 v240, v[40:41], s[18:19] offset:32
	global_store_dwordx2 v240, v[36:37], s[18:19] offset:256
	global_store_dwordx2 v240, v[32:33], s[18:19] offset:288
	s_waitcnt vmcnt(20)
	v_pk_fma_f32 v[28:29], v[28:29], 0.5, v[162:163] op_sel_hi:[1,0,1]
	v_pk_fma_f32 v[30:31], v[30:31], 0.5, v[164:165] op_sel_hi:[1,0,1]
	v_pk_fma_f32 v[24:25], v[24:25], 0.5, v[166:167] op_sel_hi:[1,0,1]
	v_pk_fma_f32 v[26:27], v[26:27], 0.5, v[168:169] op_sel_hi:[1,0,1]
	v_pk_fma_f32 v[20:21], v[20:21], 0.5, v[170:171] op_sel_hi:[1,0,1]
	v_pk_fma_f32 v[22:23], v[22:23], 0.5, v[172:173] op_sel_hi:[1,0,1]
	v_pk_fma_f32 v[16:17], v[16:17], 0.5, v[174:175] op_sel_hi:[1,0,1]
	v_pk_fma_f32 v[18:19], v[18:19], 0.5, v[176:177] op_sel_hi:[1,0,1]
	v_mul_f32_e32 v162, v29, v29
	v_mul_f32_e32 v166, v25, v25
	v_mul_f32_e32 v170, v21, v21
	v_mul_f32_e32 v174, v17, v17
	v_mul_f32_e32 v163, v31, v31
	v_mul_f32_e32 v167, v27, v27
	v_mul_f32_e32 v171, v23, v23
	v_mul_f32_e32 v175, v19, v19
	v_fmac_f32_e32 v162, v28, v28
	v_fmac_f32_e32 v166, v24, v24
	v_fmac_f32_e32 v170, v20, v20
	v_fmac_f32_e32 v174, v16, v16
	v_fmac_f32_e32 v163, v30, v30
	v_fmac_f32_e32 v167, v26, v26
	v_fmac_f32_e32 v171, v22, v22
	v_fmac_f32_e32 v175, v18, v18
	v_add_f32_e32 v162, v162, v163
	v_add_f32_e32 v166, v166, v167
	v_add_f32_e32 v170, v170, v171
	v_add_f32_e32 v174, v174, v175
	v_add_f32_e32 v236, v162, v166
	v_cvt_pk_bf16_f32 v28, v28, v29
	v_cvt_pk_bf16_f32 v29, v30, v31
	v_cvt_pk_bf16_f32 v24, v24, v25
	v_cvt_pk_bf16_f32 v25, v26, v27
	v_cvt_pk_bf16_f32 v20, v20, v21
	v_cvt_pk_bf16_f32 v21, v22, v23
	v_cvt_pk_bf16_f32 v16, v16, v17
	v_cvt_pk_bf16_f32 v17, v18, v19
	v_add_f32_e32 v236, v236, v170
	v_add_f32_e32 v236, v236, v174
	v_add_u32_e32 v240, 0xa0000, v239
	global_store_dwordx2 v240, v[28:29], s[18:19]
	global_store_dwordx2 v240, v[24:25], s[18:19] offset:32
	global_store_dwordx2 v240, v[20:21], s[18:19] offset:256
	global_store_dwordx2 v240, v[16:17], s[18:19] offset:288
	s_waitcnt vmcnt(16)
	v_pk_fma_f32 v[12:13], v[12:13], 0.5, v[180:181] op_sel_hi:[1,0,1]
	v_pk_fma_f32 v[14:15], v[14:15], 0.5, v[182:183] op_sel_hi:[1,0,1]
	v_pk_fma_f32 v[8:9], v[8:9], 0.5, v[184:185] op_sel_hi:[1,0,1]
	v_pk_fma_f32 v[10:11], v[10:11], 0.5, v[186:187] op_sel_hi:[1,0,1]
	v_pk_fma_f32 v[4:5], v[4:5], 0.5, v[192:193] op_sel_hi:[1,0,1]
	v_pk_fma_f32 v[6:7], v[6:7], 0.5, v[194:195] op_sel_hi:[1,0,1]
	v_pk_fma_f32 v[0:1], v[0:1], 0.5, v[196:197] op_sel_hi:[1,0,1]
	v_pk_fma_f32 v[2:3], v[2:3], 0.5, v[198:199] op_sel_hi:[1,0,1]
	v_mul_f32_e32 v180, v13, v13
	v_mul_f32_e32 v184, v9, v9
	v_mul_f32_e32 v192, v5, v5
	v_mul_f32_e32 v196, v1, v1
	v_mul_f32_e32 v181, v15, v15
	v_mul_f32_e32 v185, v11, v11
	v_mul_f32_e32 v193, v7, v7
	v_mul_f32_e32 v197, v3, v3
	v_fmac_f32_e32 v180, v12, v12
	v_fmac_f32_e32 v184, v8, v8
	v_fmac_f32_e32 v192, v4, v4
	v_fmac_f32_e32 v196, v0, v0
	v_fmac_f32_e32 v181, v14, v14
	v_fmac_f32_e32 v185, v10, v10
	v_fmac_f32_e32 v193, v6, v6
	v_fmac_f32_e32 v197, v2, v2
	v_add_f32_e32 v180, v180, v181
	v_add_f32_e32 v184, v184, v185
	v_add_f32_e32 v192, v192, v193
	v_add_f32_e32 v196, v196, v197
	v_add_f32_e32 v237, v180, v184
	v_cvt_pk_bf16_f32 v12, v12, v13
	v_cvt_pk_bf16_f32 v13, v14, v15
	v_cvt_pk_bf16_f32 v8, v8, v9
	v_cvt_pk_bf16_f32 v9, v10, v11
	v_cvt_pk_bf16_f32 v4, v4, v5
	v_cvt_pk_bf16_f32 v5, v6, v7
	v_cvt_pk_bf16_f32 v0, v0, v1
	v_cvt_pk_bf16_f32 v1, v2, v3
	v_add_f32_e32 v237, v237, v192
	v_add_f32_e32 v237, v237, v196
	v_add_u32_e32 v240, 0xb0000, v239
	global_store_dwordx2 v240, v[12:13], s[18:19]
	global_store_dwordx2 v240, v[8:9], s[18:19] offset:32
	global_store_dwordx2 v240, v[4:5], s[18:19] offset:256
	global_store_dwordx2 v240, v[0:1], s[18:19] offset:288
	ds_bpermute_b32 v140, v243, v188
	ds_bpermute_b32 v141, v243, v189
	ds_bpermute_b32 v150, v243, v232
	ds_bpermute_b32 v151, v243, v233
	ds_bpermute_b32 v154, v243, v234
	ds_bpermute_b32 v155, v243, v235
	ds_bpermute_b32 v158, v243, v236
	ds_bpermute_b32 v159, v243, v237
	s_waitcnt lgkmcnt(0)
	v_add_f32_e32 v188, v188, v140
	v_add_f32_e32 v189, v189, v141
	v_add_f32_e32 v232, v232, v150
	v_add_f32_e32 v233, v233, v151
	v_add_f32_e32 v234, v234, v154
	v_add_f32_e32 v235, v235, v155
	v_add_f32_e32 v236, v236, v158
	v_add_f32_e32 v237, v237, v159
	ds_bpermute_b32 v140, v244, v188
	ds_bpermute_b32 v141, v244, v189
	ds_bpermute_b32 v150, v244, v232
	ds_bpermute_b32 v151, v244, v233
	ds_bpermute_b32 v154, v244, v234
	ds_bpermute_b32 v155, v244, v235
	ds_bpermute_b32 v158, v244, v236
	ds_bpermute_b32 v159, v244, v237
	s_waitcnt lgkmcnt(0)
	v_add_f32_e32 v188, v188, v140
	v_add_f32_e32 v189, v189, v141
	v_add_f32_e32 v232, v232, v150
	v_add_f32_e32 v233, v233, v151
	v_add_f32_e32 v234, v234, v154
	v_add_f32_e32 v235, v235, v155
	v_add_f32_e32 v236, v236, v158
	v_add_f32_e32 v237, v237, v159
	v_cmp_gt_u32_e32 vcc, 16, v242
	s_and_saveexec_b64 s[26:27], vcc
	global_atomic_add_f32 v241, v188, s[90:91]
	global_atomic_add_f32 v241, v189, s[90:91] offset:64
	global_atomic_add_f32 v241, v232, s[90:91] offset:128
	global_atomic_add_f32 v241, v233, s[90:91] offset:192
	global_atomic_add_f32 v241, v234, s[90:91] offset:512
	global_atomic_add_f32 v241, v235, s[90:91] offset:576
	global_atomic_add_f32 v241, v236, s[90:91] offset:640
	global_atomic_add_f32 v241, v237, s[90:91] offset:704
	s_mov_b64 exec, s[26:27]
	s_and_b64 vcc, exec, s[6:7]
	s_mov_b64 s[6:7], -1
	s_cbranch_vccnz .LBB0_251
	s_andn2_b64 vcc, exec, s[2:3]
	s_cbranch_vccnz .LBB0_250
	s_barrier
	s_branch .LBB0_250

.LBB0_338:
	s_or_b64 exec, exec, s[2:3]
	v_mov_b32_e32 v14, v252
	s_waitcnt lgkmcnt(0)
	s_barrier
	s_cmpk_lt_i32 s95, 0x300
	v_writelane_b32 v254, s80, 44
	v_readfirstlane_b32 s5, v14
	s_cbranch_scc0 .LBB0_354
	v_lshlrev_b32_e32 v0, 4, v14
	v_add_u32_e32 v1, 0x2000, v0
	v_ashrrev_i32_e32 v2, 31, v1
	v_lshrrev_b32_e32 v2, 22, v2
	v_add_u32_e32 v2, v1, v2
	v_ashrrev_i32_e32 v8, 10, v2
	v_mul_i32_i24_e32 v2, 0x400, v8
	v_sub_u32_e32 v1, v1, v2
	v_lshrrev_b32_e32 v2, 4, v1
	v_bitop3_b32 v1, v2, v1, 32 bitop3:0x6c
	v_ashrrev_i32_e32 v2, 31, v1
	v_lshrrev_b32_e32 v2, 26, v2
	v_add_u32_e32 v2, v1, v2
	v_lshlrev_b32_e32 v3, 3, v8
	v_ashrrev_i32_e32 v9, 6, v2
	v_and_b32_e32 v3, -16, v3
	v_add_u32_e32 v3, v9, v3
	v_and_b32_e32 v4, 3, v9
	s_mov_b32 s2, 0xfffe0
	v_lshrrev_b32_e32 v5, 2, v3
	v_lshlrev_b32_e32 v6, 1, v3
	v_and_b32_e32 v2, 0xc0, v2
	v_and_or_b32 v4, v3, s2, v4
	v_and_b32_e32 v5, 4, v5
	v_and_b32_e32 v6, 24, v6
	v_sub_u32_e32 v1, v1, v2
	v_mov_b32_e32 v2, 1
	v_or3_b32 v4, v4, v5, v6
	v_lshlrev_b32_e32 v5, 5, v8
	v_ashrrev_i16_sdwa v1, v2, sext(v1) dst_sel:DWORD dst_unused:UNUSED_PAD src0_sel:DWORD src1_sel:BYTE_0
	v_and_b32_e32 v5, 32, v5
	v_bfe_i32 v10, v1, 0, 16
	v_add_lshl_u32 v1, v5, v10, 1
	v_lshl_add_u32 v128, v4, 12, v1
	v_lshl_add_u32 v130, v3, 12, v1
	v_bfe_i32 v1, v14, 27, 1
	v_lshrrev_b32_e32 v1, 22, v1
	v_add_u32_e32 v1, v0, v1
	v_and_b32_e32 v1, 0xfffffc00, v1
	v_sub_u32_e32 v0, v0, v1
	v_lshrrev_b32_e32 v1, 4, v0
	v_ashrrev_i32_e32 v3, 31, v14
	v_bitop3_b32 v0, v1, v0, 32 bitop3:0x6c
	v_lshrrev_b32_e32 v3, 26, v3
	v_ashrrev_i32_e32 v1, 31, v0
	v_add_u32_e32 v3, v14, v3
	v_lshrrev_b32_e32 v1, 26, v1
	v_ashrrev_i32_e32 v12, 6, v3
	v_add_u32_e32 v1, v0, v1
	v_lshlrev_b32_e32 v3, 3, v12
	v_ashrrev_i32_e32 v11, 6, v1
	v_and_b32_e32 v3, -16, v3
	v_add_u32_e32 v3, v11, v3
	v_and_b32_e32 v4, 3, v11
	v_and_or_b32 v4, v3, s2, v4
	s_lshr_b32 s2, s80, 29
	s_add_i32 s2, s95, s2
	s_ashr_i32 s6, s5, 6
	s_ashr_i32 s3, s2, 3
	s_and_b32 s2, s2, -8
	s_ashr_i32 s7, s5, 8
	s_lshl_b32 s20, s6, 10
	s_sub_i32 s2, s95, s2
	s_cmp_lt_i32 s2, 0
	s_movk_i32 s21, 0x61
	s_cselect_b32 s4, s21, 0x60
	s_mul_i32 s2, s2, s4
	s_add_i32 s2, s2, s3
	s_mul_hi_i32 s3, s2, 0x2aaaaaab
	s_lshr_b32 s4, s3, 31
	s_ashr_i32 s3, s3, 5
	s_add_i32 s3, s3, s4
	s_lshl_b32 s8, s3, 3
	s_mulk_i32 s3, 0xc0
	s_sub_i32 s2, s2, s3
	s_sext_i32_i16 s3, s2
	s_bfe_u32 s3, s3, 0x3001c
	s_add_i32 s3, s2, s3
	s_sext_i32_i16 s4, s3
	s_and_b32 s3, s3, 0xfff8
	s_sub_i32 s2, s2, s3
	s_sext_i32_i16 s2, s2
	v_lshrrev_b32_e32 v5, 2, v3
	v_lshlrev_b32_e32 v6, 1, v3
	v_and_b32_e32 v1, 0xc0, v1
	s_lshr_b32 s4, s4, 3
	s_add_i32 s28, s8, s2
	v_and_b32_e32 v5, 4, v5
	v_and_b32_e32 v6, 24, v6
	v_sub_u32_e32 v0, v0, v1
	s_ashr_i32 s29, s28, 31
	s_bfe_i64 s[8:9], s[4:5], 0x100000
	v_or3_b32 v4, v4, v5, v6
	v_lshlrev_b32_e32 v5, 5, v12
	v_ashrrev_i16_sdwa v0, v2, sext(v0) dst_sel:DWORD dst_unused:UNUSED_PAD src0_sel:DWORD src1_sel:BYTE_0
	s_lshl_b64 s[2:3], s[28:29], 20
	s_lshl_b64 s[8:9], s[8:9], 20
	v_and_b32_e32 v5, 32, v5
	v_bfe_i32 v13, v0, 0, 16
	s_add_u32 s82, s0, s8
	v_add_lshl_u32 v0, v5, v13, 1
	s_addc_u32 s83, s1, s9
	s_add_i32 s22, s20, 0
	v_lshl_add_u32 v132, v4, 12, v0
	v_and_b32_e32 v238, 15, v14
	v_lshl_or_b32 v238, s7, 6, v238
	v_lshl_add_u32 v238, s28, 8, v238
	v_lshlrev_b32_e32 v238, 2, v238
	global_load_dword v230, v238, s[90:91]
	global_load_dword v231, v238, s[90:91] offset:64
	global_load_dword v232, v238, s[90:91] offset:128
	global_load_dword v233, v238, s[90:91] offset:192
	global_load_dword v234, v238, s[90:91] offset:512
	global_load_dword v235, v238, s[90:91] offset:576
	global_load_dword v236, v238, s[90:91] offset:640
	global_load_dword v237, v238, s[90:91] offset:704
	s_add_i32 m0, s22, 0x10000
	v_lshl_add_u32 v134, v3, 12, v0
	global_load_lds_dwordx4 v132, s[82:83]
	s_add_i32 m0, s22, 0x12000
	s_add_u32 s8, s82, 0x80000
	global_load_lds_dwordx4 v128, s[82:83]
	s_addc_u32 s9, s83, 0
	s_add_i32 m0, s22, 0x14000
	v_mov_b32_e32 v133, 0
	global_load_lds_dwordx4 v132, s[8:9]
	s_add_i32 m0, s22, 0x16000
	s_add_u32 s80, s18, s2
	s_addc_u32 s81, s19, s3
	s_add_i32 s23, s22, 0x2000
	global_load_lds_dwordx4 v128, s[8:9]
	s_mov_b32 m0, s22
	s_add_u32 s2, s80, 0x80000
	global_load_lds_dwordx4 v134, s[80:81]
	s_mov_b32 m0, s23
	s_addc_u32 s3, s81, 0
	s_add_i32 s24, s22, 0x4000
	global_load_lds_dwordx4 v130, s[80:81]
	s_mov_b32 m0, s24
	s_add_i32 s25, s22, 0x6000
	global_load_lds_dwordx4 v134, s[2:3]
	s_mov_b32 m0, s25
	v_mov_b32_e32 v129, v133
	global_load_lds_dwordx4 v130, s[2:3]
	v_mov_b32_e32 v135, v133
	v_mov_b32_e32 v131, v133
	s_cmp_eq_u32 s7, 1
	s_mov_b32 s33, 0
	v_lshl_add_u64 v[6:7], s[82:83], 0, v[132:133]
	v_lshl_add_u64 v[4:5], s[82:83], 0, v[128:129]
	v_lshl_add_u64 v[0:1], s[80:81], 0, v[134:135]
	s_cselect_b64 s[2:3], -1, 0
	s_cmp_lg_u32 s7, 1
	v_lshl_add_u64 v[2:3], s[80:81], 0, v[130:131]
	s_cbranch_scc1 .LBB0_341
	s_barrier

.LBB0_350:
	s_waitcnt vmcnt(8)
	v_fmamk_f32 v158, v230, 0x3a000000, v156
	v_fmamk_f32 v159, v231, 0x3a000000, v156
	v_fmamk_f32 v160, v232, 0x3a000000, v156
	v_fmamk_f32 v161, v233, 0x3a000000, v156
	v_fmamk_f32 v162, v234, 0x3a000000, v156
	v_fmamk_f32 v163, v235, 0x3a000000, v156
	v_fmamk_f32 v164, v236, 0x3a000000, v156
	v_fmamk_f32 v165, v237, 0x3a000000, v156
	v_rsq_f32_e32 v158, v158
	v_rsq_f32_e32 v159, v159
	v_rsq_f32_e32 v160, v160
	v_rsq_f32_e32 v161, v161
	v_rsq_f32_e32 v162, v162
	v_rsq_f32_e32 v163, v163
	v_rsq_f32_e32 v164, v164
	v_rsq_f32_e32 v165, v165
	v_lshl_add_u32 v144, s28, 8, v150
	s_lshl_b32 s11, s29, 8
	s_add_i32 s13, s11, 0xfffff400
	s_cmp_lt_i32 s29, 12
	s_cselect_b32 s11, s11, s13
	s_mov_b32 s13, 0x10200000
	s_cselect_b32 s13, s13, 0x13200000
	v_or_b32_e32 v146, s11, v152
	v_mul_u32_u24_e32 v145, 0x1800, v144
	v_lshl_add_u32 v180, v146, 1, v145
	v_add_u32_e32 v180, s13, v180
	v_add_u32_e32 v181, 0x18000, v180
	v_add_u32_e32 v182, 0x30000, v180
	v_add_u32_e32 v183, 0x48000, v180
	v_add_u32_e32 v184, 0xc0000, v180
	v_add_u32_e32 v185, 0xd8000, v180
	v_add_u32_e32 v186, 0xf0000, v180
	v_add_u32_e32 v187, 0x108000, v180
	s_and_b64 vcc, exec, s[4:5]
	s_cselect_b32 s28, s12, s28
	v_lshl_add_u32 v144, s28, 8, v150
	v_lshlrev_b32_e32 v144, 2, v144
	global_load_dword v230, v144, s[90:91]
	global_load_dword v231, v144, s[90:91] offset:64
	global_load_dword v232, v144, s[90:91] offset:128
	global_load_dword v233, v144, s[90:91] offset:192
	global_load_dword v234, v144, s[90:91] offset:512
	global_load_dword v235, v144, s[90:91] offset:576
	global_load_dword v236, v144, s[90:91] offset:640
	global_load_dword v237, v144, s[90:91] offset:704
	v_pk_mul_f32 v[124:125], v[124:125], v[158:159] op_sel_hi:[1,0]
	v_pk_mul_f32 v[126:127], v[126:127], v[158:159] op_sel_hi:[1,0]
	v_pk_mul_f32 v[120:121], v[120:121], v[158:159] op_sel_hi:[1,0]
	v_pk_mul_f32 v[122:123], v[122:123], v[158:159] op_sel_hi:[1,0]
	v_pk_mul_f32 v[116:117], v[116:117], v[158:159] op_sel_hi:[1,0]
	v_pk_mul_f32 v[118:119], v[118:119], v[158:159] op_sel_hi:[1,0]
	v_pk_mul_f32 v[112:113], v[112:113], v[158:159] op_sel_hi:[1,0]
	v_pk_mul_f32 v[114:115], v[114:115], v[158:159] op_sel_hi:[1,0]
	v_cvt_pk_bf16_f32 v124, v124, v125
	v_cvt_pk_bf16_f32 v125, v126, v127
	v_cvt_pk_bf16_f32 v126, v120, v121
	v_cvt_pk_bf16_f32 v127, v122, v123
	global_store_dwordx4 v180, v[124:127], s[78:79]
	v_cvt_pk_bf16_f32 v116, v116, v117
	v_cvt_pk_bf16_f32 v117, v118, v119
	v_cvt_pk_bf16_f32 v118, v112, v113
	v_cvt_pk_bf16_f32 v119, v114, v115
	global_store_dwordx4 v180, v[116:119], s[78:79] offset:256
	v_pk_mul_f32 v[108:109], v[108:109], v[158:159] op_sel:[0,1] op_sel_hi:[1,1]
	v_pk_mul_f32 v[110:111], v[110:111], v[158:159] op_sel:[0,1] op_sel_hi:[1,1]
	v_pk_mul_f32 v[104:105], v[104:105], v[158:159] op_sel:[0,1] op_sel_hi:[1,1]
	v_pk_mul_f32 v[106:107], v[106:107], v[158:159] op_sel:[0,1] op_sel_hi:[1,1]
	v_pk_mul_f32 v[100:101], v[100:101], v[158:159] op_sel:[0,1] op_sel_hi:[1,1]
	v_pk_mul_f32 v[102:103], v[102:103], v[158:159] op_sel:[0,1] op_sel_hi:[1,1]
	v_pk_mul_f32 v[96:97], v[96:97], v[158:159] op_sel:[0,1] op_sel_hi:[1,1]
	v_pk_mul_f32 v[98:99], v[98:99], v[158:159] op_sel:[0,1] op_sel_hi:[1,1]
	v_cvt_pk_bf16_f32 v108, v108, v109
	v_cvt_pk_bf16_f32 v109, v110, v111
	v_cvt_pk_bf16_f32 v110, v104, v105
	v_cvt_pk_bf16_f32 v111, v106, v107
	global_store_dwordx4 v181, v[108:111], s[78:79]
	v_cvt_pk_bf16_f32 v100, v100, v101
	v_cvt_pk_bf16_f32 v101, v102, v103
	v_cvt_pk_bf16_f32 v102, v96, v97
	v_cvt_pk_bf16_f32 v103, v98, v99
	global_store_dwordx4 v181, v[100:103], s[78:79] offset:256
	v_pk_mul_f32 v[92:93], v[92:93], v[160:161] op_sel_hi:[1,0]
	v_pk_mul_f32 v[94:95], v[94:95], v[160:161] op_sel_hi:[1,0]
	v_pk_mul_f32 v[88:89], v[88:89], v[160:161] op_sel_hi:[1,0]
	v_pk_mul_f32 v[90:91], v[90:91], v[160:161] op_sel_hi:[1,0]
	v_pk_mul_f32 v[84:85], v[84:85], v[160:161] op_sel_hi:[1,0]
	v_pk_mul_f32 v[86:87], v[86:87], v[160:161] op_sel_hi:[1,0]
	v_pk_mul_f32 v[80:81], v[80:81], v[160:161] op_sel_hi:[1,0]
	v_pk_mul_f32 v[82:83], v[82:83], v[160:161] op_sel_hi:[1,0]
	v_cvt_pk_bf16_f32 v92, v92, v93
	v_cvt_pk_bf16_f32 v93, v94, v95
	v_cvt_pk_bf16_f32 v94, v88, v89
	v_cvt_pk_bf16_f32 v95, v90, v91
	global_store_dwordx4 v182, v[92:95], s[78:79]
	v_cvt_pk_bf16_f32 v84, v84, v85
	v_cvt_pk_bf16_f32 v85, v86, v87
	v_cvt_pk_bf16_f32 v86, v80, v81
	v_cvt_pk_bf16_f32 v87, v82, v83
	global_store_dwordx4 v182, v[84:87], s[78:79] offset:256
	v_pk_mul_f32 v[76:77], v[76:77], v[160:161] op_sel:[0,1] op_sel_hi:[1,1]
	v_pk_mul_f32 v[78:79], v[78:79], v[160:161] op_sel:[0,1] op_sel_hi:[1,1]
	v_pk_mul_f32 v[72:73], v[72:73], v[160:161] op_sel:[0,1] op_sel_hi:[1,1]
	v_pk_mul_f32 v[74:75], v[74:75], v[160:161] op_sel:[0,1] op_sel_hi:[1,1]
	v_pk_mul_f32 v[68:69], v[68:69], v[160:161] op_sel:[0,1] op_sel_hi:[1,1]
	v_pk_mul_f32 v[70:71], v[70:71], v[160:161] op_sel:[0,1] op_sel_hi:[1,1]
	v_pk_mul_f32 v[64:65], v[64:65], v[160:161] op_sel:[0,1] op_sel_hi:[1,1]
	v_pk_mul_f32 v[66:67], v[66:67], v[160:161] op_sel:[0,1] op_sel_hi:[1,1]
	v_cvt_pk_bf16_f32 v76, v76, v77
	v_cvt_pk_bf16_f32 v77, v78, v79
	v_cvt_pk_bf16_f32 v78, v72, v73
	v_cvt_pk_bf16_f32 v79, v74, v75
	global_store_dwordx4 v183, v[76:79], s[78:79]
	v_cvt_pk_bf16_f32 v68, v68, v69
	v_cvt_pk_bf16_f32 v69, v70, v71
	v_cvt_pk_bf16_f32 v70, v64, v65
	v_cvt_pk_bf16_f32 v71, v66, v67
	global_store_dwordx4 v183, v[68:71], s[78:79] offset:256
	v_pk_mul_f32 v[60:61], v[60:61], v[162:163] op_sel_hi:[1,0]
	v_pk_mul_f32 v[62:63], v[62:63], v[162:163] op_sel_hi:[1,0]
	v_pk_mul_f32 v[56:57], v[56:57], v[162:163] op_sel_hi:[1,0]
	v_pk_mul_f32 v[58:59], v[58:59], v[162:163] op_sel_hi:[1,0]
	v_pk_mul_f32 v[52:53], v[52:53], v[162:163] op_sel_hi:[1,0]
	v_pk_mul_f32 v[54:55], v[54:55], v[162:163] op_sel_hi:[1,0]
	v_pk_mul_f32 v[48:49], v[48:49], v[162:163] op_sel_hi:[1,0]
	v_pk_mul_f32 v[50:51], v[50:51], v[162:163] op_sel_hi:[1,0]
	v_cvt_pk_bf16_f32 v60, v60, v61
	v_cvt_pk_bf16_f32 v61, v62, v63
	v_cvt_pk_bf16_f32 v62, v56, v57
	v_cvt_pk_bf16_f32 v63, v58, v59
	global_store_dwordx4 v184, v[60:63], s[78:79]
	v_cvt_pk_bf16_f32 v52, v52, v53
	v_cvt_pk_bf16_f32 v53, v54, v55
	v_cvt_pk_bf16_f32 v54, v48, v49
	v_cvt_pk_bf16_f32 v55, v50, v51
	global_store_dwordx4 v184, v[52:55], s[78:79] offset:256
	v_pk_mul_f32 v[44:45], v[44:45], v[162:163] op_sel:[0,1] op_sel_hi:[1,1]
	v_pk_mul_f32 v[46:47], v[46:47], v[162:163] op_sel:[0,1] op_sel_hi:[1,1]
	v_pk_mul_f32 v[40:41], v[40:41], v[162:163] op_sel:[0,1] op_sel_hi:[1,1]
	v_pk_mul_f32 v[42:43], v[42:43], v[162:163] op_sel:[0,1] op_sel_hi:[1,1]
	v_pk_mul_f32 v[36:37], v[36:37], v[162:163] op_sel:[0,1] op_sel_hi:[1,1]
	v_pk_mul_f32 v[38:39], v[38:39], v[162:163] op_sel:[0,1] op_sel_hi:[1,1]
	v_pk_mul_f32 v[32:33], v[32:33], v[162:163] op_sel:[0,1] op_sel_hi:[1,1]
	v_pk_mul_f32 v[34:35], v[34:35], v[162:163] op_sel:[0,1] op_sel_hi:[1,1]
	v_cvt_pk_bf16_f32 v44, v44, v45
	v_cvt_pk_bf16_f32 v45, v46, v47
	v_cvt_pk_bf16_f32 v46, v40, v41
	v_cvt_pk_bf16_f32 v47, v42, v43
	global_store_dwordx4 v185, v[44:47], s[78:79]
	v_cvt_pk_bf16_f32 v36, v36, v37
	v_cvt_pk_bf16_f32 v37, v38, v39
	v_cvt_pk_bf16_f32 v38, v32, v33
	v_cvt_pk_bf16_f32 v39, v34, v35
	global_store_dwordx4 v185, v[36:39], s[78:79] offset:256
	v_pk_mul_f32 v[28:29], v[28:29], v[164:165] op_sel_hi:[1,0]
	v_pk_mul_f32 v[30:31], v[30:31], v[164:165] op_sel_hi:[1,0]
	v_pk_mul_f32 v[24:25], v[24:25], v[164:165] op_sel_hi:[1,0]
	v_pk_mul_f32 v[26:27], v[26:27], v[164:165] op_sel_hi:[1,0]
	v_pk_mul_f32 v[20:21], v[20:21], v[164:165] op_sel_hi:[1,0]
	v_pk_mul_f32 v[22:23], v[22:23], v[164:165] op_sel_hi:[1,0]
	v_pk_mul_f32 v[16:17], v[16:17], v[164:165] op_sel_hi:[1,0]
	v_pk_mul_f32 v[18:19], v[18:19], v[164:165] op_sel_hi:[1,0]
	v_cvt_pk_bf16_f32 v28, v28, v29
	v_cvt_pk_bf16_f32 v29, v30, v31
	v_cvt_pk_bf16_f32 v30, v24, v25
	v_cvt_pk_bf16_f32 v31, v26, v27
	global_store_dwordx4 v186, v[28:31], s[78:79]
	v_cvt_pk_bf16_f32 v20, v20, v21
	v_cvt_pk_bf16_f32 v21, v22, v23
	v_cvt_pk_bf16_f32 v22, v16, v17
	v_cvt_pk_bf16_f32 v23, v18, v19
	global_store_dwordx4 v186, v[20:23], s[78:79] offset:256
	v_pk_mul_f32 v[12:13], v[12:13], v[164:165] op_sel:[0,1] op_sel_hi:[1,1]
	v_pk_mul_f32 v[14:15], v[14:15], v[164:165] op_sel:[0,1] op_sel_hi:[1,1]
	v_pk_mul_f32 v[8:9], v[8:9], v[164:165] op_sel:[0,1] op_sel_hi:[1,1]
	v_pk_mul_f32 v[10:11], v[10:11], v[164:165] op_sel:[0,1] op_sel_hi:[1,1]
	v_pk_mul_f32 v[4:5], v[4:5], v[164:165] op_sel:[0,1] op_sel_hi:[1,1]
	v_pk_mul_f32 v[6:7], v[6:7], v[164:165] op_sel:[0,1] op_sel_hi:[1,1]
	v_pk_mul_f32 v[0:1], v[0:1], v[164:165] op_sel:[0,1] op_sel_hi:[1,1]
	v_pk_mul_f32 v[2:3], v[2:3], v[164:165] op_sel:[0,1] op_sel_hi:[1,1]
	v_cvt_pk_bf16_f32 v12, v12, v13
	v_cvt_pk_bf16_f32 v13, v14, v15
	v_cvt_pk_bf16_f32 v14, v8, v9
	v_cvt_pk_bf16_f32 v15, v10, v11
	global_store_dwordx4 v187, v[12:15], s[78:79]
	v_cvt_pk_bf16_f32 v4, v4, v5
	v_cvt_pk_bf16_f32 v5, v6, v7
	v_cvt_pk_bf16_f32 v6, v0, v1
	v_cvt_pk_bf16_f32 v7, v2, v3
	s_andn2_b64 vcc, exec, s[4:5]
	s_mov_b64 s[28:29], -1
	global_store_dwordx4 v187, v[4:7], s[78:79] offset:256
	s_cbranch_vccnz .LBB0_343
	s_andn2_b64 vcc, exec, s[2:3]
	s_cbranch_vccnz .LBB0_342
	s_barrier
	s_branch .LBB0_342

.LBB0_858:
	v_lshl_add_u32 v207, s28, 8, v144
	v_lshl_or_b32 v202, s30, 8, v146
	v_lshl_add_u32 v201, v207, 11, v202
	v_lshlrev_b32_e32 v200, 1, v201
	v_lshlrev_b32_e32 v201, 1, v201
	v_lshlrev_b32_e32 v203, 2, v207
	v_mov_b32_e32 v202, v200
	global_load_dwordx2 v[140:141], v202, s[18:19]
	global_load_dwordx2 v[142:143], v202, s[18:19] offset:32
	global_load_dwordx2 v[150:151], v202, s[18:19] offset:256
	global_load_dwordx2 v[152:153], v202, s[18:19] offset:288
	v_add_u32_e32 v202, 0x10000, v200
	global_load_dwordx2 v[154:155], v202, s[18:19]
	global_load_dwordx2 v[156:157], v202, s[18:19] offset:32
	global_load_dwordx2 v[158:159], v202, s[18:19] offset:256
	global_load_dwordx2 v[160:161], v202, s[18:19] offset:288
	v_add_u32_e32 v202, 0x20000, v200
	global_load_dwordx2 v[162:163], v202, s[18:19]
	global_load_dwordx2 v[164:165], v202, s[18:19] offset:32
	global_load_dwordx2 v[166:167], v202, s[18:19] offset:256
	global_load_dwordx2 v[168:169], v202, s[18:19] offset:288
	v_add_u32_e32 v202, 0x30000, v200
	global_load_dwordx2 v[170:171], v202, s[18:19]
	global_load_dwordx2 v[172:173], v202, s[18:19] offset:32
	global_load_dwordx2 v[174:175], v202, s[18:19] offset:256
	global_load_dwordx2 v[176:177], v202, s[18:19] offset:288
	v_add_u32_e32 v202, 0x80000, v200
	global_load_dwordx2 v[180:181], v202, s[18:19]
	global_load_dwordx2 v[182:183], v202, s[18:19] offset:32
	global_load_dwordx2 v[184:185], v202, s[18:19] offset:256
	global_load_dwordx2 v[186:187], v202, s[18:19] offset:288
	v_mbcnt_lo_u32_b32 v204, -1, 0
	v_mbcnt_hi_u32_b32 v204, -1, v204
	v_xor_b32_e32 v205, 16, v204
	v_xor_b32_e32 v206, 32, v204
	v_lshlrev_b32_e32 v205, 2, v205
	v_lshlrev_b32_e32 v206, 2, v206
	s_waitcnt vmcnt(16)
	v_lshlrev_b32_e32 v188, 16, v140
	v_and_b32_e32 v189, 0xffff0000, v140
	v_lshlrev_b32_e32 v190, 16, v141
	v_and_b32_e32 v191, 0xffff0000, v141
	v_pk_add_f32 v[124:125], v[124:125], v[188:189]
	v_pk_add_f32 v[126:127], v[126:127], v[190:191]
	v_lshlrev_b32_e32 v188, 16, v142
	v_and_b32_e32 v189, 0xffff0000, v142
	v_lshlrev_b32_e32 v190, 16, v143
	v_and_b32_e32 v191, 0xffff0000, v143
	v_pk_add_f32 v[120:121], v[120:121], v[188:189]
	v_pk_add_f32 v[122:123], v[122:123], v[190:191]
	v_lshlrev_b32_e32 v188, 16, v150
	v_and_b32_e32 v189, 0xffff0000, v150
	v_lshlrev_b32_e32 v190, 16, v151
	v_and_b32_e32 v191, 0xffff0000, v151
	v_pk_add_f32 v[116:117], v[116:117], v[188:189]
	v_pk_add_f32 v[118:119], v[118:119], v[190:191]
	v_lshlrev_b32_e32 v188, 16, v152
	v_and_b32_e32 v189, 0xffff0000, v152
	v_lshlrev_b32_e32 v190, 16, v153
	v_and_b32_e32 v191, 0xffff0000, v153
	v_pk_add_f32 v[112:113], v[112:113], v[188:189]
	v_pk_add_f32 v[114:115], v[114:115], v[190:191]
	v_mul_f32_e32 v140, v125, v125
	v_mul_f32_e32 v142, v121, v121
	v_mul_f32_e32 v150, v117, v117
	v_mul_f32_e32 v152, v113, v113
	v_mul_f32_e32 v141, v127, v127
	v_mul_f32_e32 v143, v123, v123
	v_mul_f32_e32 v151, v119, v119
	v_mul_f32_e32 v153, v115, v115
	v_fmac_f32_e32 v140, v124, v124
	v_fmac_f32_e32 v142, v120, v120
	v_fmac_f32_e32 v150, v116, v116
	v_fmac_f32_e32 v152, v112, v112
	v_fmac_f32_e32 v141, v126, v126
	v_fmac_f32_e32 v143, v122, v122
	v_fmac_f32_e32 v151, v118, v118
	v_fmac_f32_e32 v153, v114, v114
	v_add_f32_e32 v140, v140, v141
	v_add_f32_e32 v142, v142, v143
	v_add_f32_e32 v150, v150, v151
	v_add_f32_e32 v152, v152, v153
	v_add_f32_e32 v192, v140, v142
	v_cvt_pk_bf16_f32 v124, v124, v125
	v_cvt_pk_bf16_f32 v125, v126, v127
	v_cvt_pk_bf16_f32 v120, v120, v121
	v_cvt_pk_bf16_f32 v121, v122, v123
	v_cvt_pk_bf16_f32 v116, v116, v117
	v_cvt_pk_bf16_f32 v117, v118, v119
	v_cvt_pk_bf16_f32 v112, v112, v113
	v_cvt_pk_bf16_f32 v113, v114, v115
	v_add_f32_e32 v192, v192, v150
	v_add_f32_e32 v192, v192, v152
	v_mov_b32_e32 v202, v201
	global_store_dwordx2 v202, v[124:125], s[18:19]
	global_store_dwordx2 v202, v[120:121], s[18:19] offset:32
	global_store_dwordx2 v202, v[116:117], s[18:19] offset:256
	global_store_dwordx2 v202, v[112:113], s[18:19] offset:288
	v_add_u32_e32 v202, 0x90000, v200
	global_load_dwordx2 v[140:141], v202, s[18:19]
	global_load_dwordx2 v[142:143], v202, s[18:19] offset:32
	global_load_dwordx2 v[150:151], v202, s[18:19] offset:256
	global_load_dwordx2 v[152:153], v202, s[18:19] offset:288
	s_waitcnt vmcnt(20)
	v_lshlrev_b32_e32 v188, 16, v154
	v_and_b32_e32 v189, 0xffff0000, v154
	v_lshlrev_b32_e32 v190, 16, v155
	v_and_b32_e32 v191, 0xffff0000, v155
	v_pk_add_f32 v[108:109], v[108:109], v[188:189]
	v_pk_add_f32 v[110:111], v[110:111], v[190:191]
	v_lshlrev_b32_e32 v188, 16, v156
	v_and_b32_e32 v189, 0xffff0000, v156
	v_lshlrev_b32_e32 v190, 16, v157
	v_and_b32_e32 v191, 0xffff0000, v157
	v_pk_add_f32 v[104:105], v[104:105], v[188:189]
	v_pk_add_f32 v[106:107], v[106:107], v[190:191]
	v_lshlrev_b32_e32 v188, 16, v158
	v_and_b32_e32 v189, 0xffff0000, v158
	v_lshlrev_b32_e32 v190, 16, v159
	v_and_b32_e32 v191, 0xffff0000, v159
	v_pk_add_f32 v[100:101], v[100:101], v[188:189]
	v_pk_add_f32 v[102:103], v[102:103], v[190:191]
	v_lshlrev_b32_e32 v188, 16, v160
	v_and_b32_e32 v189, 0xffff0000, v160
	v_lshlrev_b32_e32 v190, 16, v161
	v_and_b32_e32 v191, 0xffff0000, v161
	v_pk_add_f32 v[96:97], v[96:97], v[188:189]
	v_pk_add_f32 v[98:99], v[98:99], v[190:191]
	v_mul_f32_e32 v154, v109, v109
	v_mul_f32_e32 v156, v105, v105
	v_mul_f32_e32 v158, v101, v101
	v_mul_f32_e32 v160, v97, v97
	v_mul_f32_e32 v155, v111, v111
	v_mul_f32_e32 v157, v107, v107
	v_mul_f32_e32 v159, v103, v103
	v_mul_f32_e32 v161, v99, v99
	v_fmac_f32_e32 v154, v108, v108
	v_fmac_f32_e32 v156, v104, v104
	v_fmac_f32_e32 v158, v100, v100
	v_fmac_f32_e32 v160, v96, v96
	v_fmac_f32_e32 v155, v110, v110
	v_fmac_f32_e32 v157, v106, v106
	v_fmac_f32_e32 v159, v102, v102
	v_fmac_f32_e32 v161, v98, v98
	v_add_f32_e32 v154, v154, v155
	v_add_f32_e32 v156, v156, v157
	v_add_f32_e32 v158, v158, v159
	v_add_f32_e32 v160, v160, v161
	v_add_f32_e32 v193, v154, v156
	v_cvt_pk_bf16_f32 v108, v108, v109
	v_cvt_pk_bf16_f32 v109, v110, v111
	v_cvt_pk_bf16_f32 v104, v104, v105
	v_cvt_pk_bf16_f32 v105, v106, v107
	v_cvt_pk_bf16_f32 v100, v100, v101
	v_cvt_pk_bf16_f32 v101, v102, v103
	v_cvt_pk_bf16_f32 v96, v96, v97
	v_cvt_pk_bf16_f32 v97, v98, v99
	v_add_f32_e32 v193, v193, v158
	v_add_f32_e32 v193, v193, v160
	v_add_u32_e32 v202, 0x10000, v201
	global_store_dwordx2 v202, v[108:109], s[18:19]
	global_store_dwordx2 v202, v[104:105], s[18:19] offset:32
	global_store_dwordx2 v202, v[100:101], s[18:19] offset:256
	global_store_dwordx2 v202, v[96:97], s[18:19] offset:288
	v_add_u32_e32 v202, 0xa0000, v200
	global_load_dwordx2 v[154:155], v202, s[18:19]
	global_load_dwordx2 v[156:157], v202, s[18:19] offset:32
	global_load_dwordx2 v[158:159], v202, s[18:19] offset:256
	global_load_dwordx2 v[160:161], v202, s[18:19] offset:288
	s_waitcnt vmcnt(24)
	v_lshlrev_b32_e32 v188, 16, v162
	v_and_b32_e32 v189, 0xffff0000, v162
	v_lshlrev_b32_e32 v190, 16, v163
	v_and_b32_e32 v191, 0xffff0000, v163
	v_pk_add_f32 v[92:93], v[92:93], v[188:189]
	v_pk_add_f32 v[94:95], v[94:95], v[190:191]
	v_lshlrev_b32_e32 v188, 16, v164
	v_and_b32_e32 v189, 0xffff0000, v164
	v_lshlrev_b32_e32 v190, 16, v165
	v_and_b32_e32 v191, 0xffff0000, v165
	v_pk_add_f32 v[88:89], v[88:89], v[188:189]
	v_pk_add_f32 v[90:91], v[90:91], v[190:191]
	v_lshlrev_b32_e32 v188, 16, v166
	v_and_b32_e32 v189, 0xffff0000, v166
	v_lshlrev_b32_e32 v190, 16, v167
	v_and_b32_e32 v191, 0xffff0000, v167
	v_pk_add_f32 v[84:85], v[84:85], v[188:189]
	v_pk_add_f32 v[86:87], v[86:87], v[190:191]
	v_lshlrev_b32_e32 v188, 16, v168
	v_and_b32_e32 v189, 0xffff0000, v168
	v_lshlrev_b32_e32 v190, 16, v169
	v_and_b32_e32 v191, 0xffff0000, v169
	v_pk_add_f32 v[80:81], v[80:81], v[188:189]
	v_pk_add_f32 v[82:83], v[82:83], v[190:191]
	v_mul_f32_e32 v162, v93, v93
	v_mul_f32_e32 v164, v89, v89
	v_mul_f32_e32 v166, v85, v85
	v_mul_f32_e32 v168, v81, v81
	v_mul_f32_e32 v163, v95, v95
	v_mul_f32_e32 v165, v91, v91
	v_mul_f32_e32 v167, v87, v87
	v_mul_f32_e32 v169, v83, v83
	v_fmac_f32_e32 v162, v92, v92
	v_fmac_f32_e32 v164, v88, v88
	v_fmac_f32_e32 v166, v84, v84
	v_fmac_f32_e32 v168, v80, v80
	v_fmac_f32_e32 v163, v94, v94
	v_fmac_f32_e32 v165, v90, v90
	v_fmac_f32_e32 v167, v86, v86
	v_fmac_f32_e32 v169, v82, v82
	v_add_f32_e32 v162, v162, v163
	v_add_f32_e32 v164, v164, v165
	v_add_f32_e32 v166, v166, v167
	v_add_f32_e32 v168, v168, v169
	v_add_f32_e32 v194, v162, v164
	v_cvt_pk_bf16_f32 v92, v92, v93
	v_cvt_pk_bf16_f32 v93, v94, v95
	v_cvt_pk_bf16_f32 v88, v88, v89
	v_cvt_pk_bf16_f32 v89, v90, v91
	v_cvt_pk_bf16_f32 v84, v84, v85
	v_cvt_pk_bf16_f32 v85, v86, v87
	v_cvt_pk_bf16_f32 v80, v80, v81
	v_cvt_pk_bf16_f32 v81, v82, v83
	v_add_f32_e32 v194, v194, v166
	v_add_f32_e32 v194, v194, v168
	v_add_u32_e32 v202, 0x20000, v201
	global_store_dwordx2 v202, v[92:93], s[18:19]
	global_store_dwordx2 v202, v[88:89], s[18:19] offset:32
	global_store_dwordx2 v202, v[84:85], s[18:19] offset:256
	global_store_dwordx2 v202, v[80:81], s[18:19] offset:288
	v_add_u32_e32 v202, 0xb0000, v200
	global_load_dwordx2 v[162:163], v202, s[18:19]
	global_load_dwordx2 v[164:165], v202, s[18:19] offset:32
	global_load_dwordx2 v[166:167], v202, s[18:19] offset:256
	global_load_dwordx2 v[168:169], v202, s[18:19] offset:288
	s_waitcnt vmcnt(28)
	v_lshlrev_b32_e32 v188, 16, v170
	v_and_b32_e32 v189, 0xffff0000, v170
	v_lshlrev_b32_e32 v190, 16, v171
	v_and_b32_e32 v191, 0xffff0000, v171
	v_pk_add_f32 v[76:77], v[76:77], v[188:189]
	v_pk_add_f32 v[78:79], v[78:79], v[190:191]
	v_lshlrev_b32_e32 v188, 16, v172
	v_and_b32_e32 v189, 0xffff0000, v172
	v_lshlrev_b32_e32 v190, 16, v173
	v_and_b32_e32 v191, 0xffff0000, v173
	v_pk_add_f32 v[72:73], v[72:73], v[188:189]
	v_pk_add_f32 v[74:75], v[74:75], v[190:191]
	v_lshlrev_b32_e32 v188, 16, v174
	v_and_b32_e32 v189, 0xffff0000, v174
	v_lshlrev_b32_e32 v190, 16, v175
	v_and_b32_e32 v191, 0xffff0000, v175
	v_pk_add_f32 v[68:69], v[68:69], v[188:189]
	v_pk_add_f32 v[70:71], v[70:71], v[190:191]
	v_lshlrev_b32_e32 v188, 16, v176
	v_and_b32_e32 v189, 0xffff0000, v176
	v_lshlrev_b32_e32 v190, 16, v177
	v_and_b32_e32 v191, 0xffff0000, v177
	v_pk_add_f32 v[64:65], v[64:65], v[188:189]
	v_pk_add_f32 v[66:67], v[66:67], v[190:191]
	v_mul_f32_e32 v170, v77, v77
	v_mul_f32_e32 v172, v73, v73
	v_mul_f32_e32 v174, v69, v69
	v_mul_f32_e32 v176, v65, v65
	v_mul_f32_e32 v171, v79, v79
	v_mul_f32_e32 v173, v75, v75
	v_mul_f32_e32 v175, v71, v71
	v_mul_f32_e32 v177, v67, v67
	v_fmac_f32_e32 v170, v76, v76
	v_fmac_f32_e32 v172, v72, v72
	v_fmac_f32_e32 v174, v68, v68
	v_fmac_f32_e32 v176, v64, v64
	v_fmac_f32_e32 v171, v78, v78
	v_fmac_f32_e32 v173, v74, v74
	v_fmac_f32_e32 v175, v70, v70
	v_fmac_f32_e32 v177, v66, v66
	v_add_f32_e32 v170, v170, v171
	v_add_f32_e32 v172, v172, v173
	v_add_f32_e32 v174, v174, v175
	v_add_f32_e32 v176, v176, v177
	v_add_f32_e32 v195, v170, v172
	v_cvt_pk_bf16_f32 v76, v76, v77
	v_cvt_pk_bf16_f32 v77, v78, v79
	v_cvt_pk_bf16_f32 v72, v72, v73
	v_cvt_pk_bf16_f32 v73, v74, v75
	v_cvt_pk_bf16_f32 v68, v68, v69
	v_cvt_pk_bf16_f32 v69, v70, v71
	v_cvt_pk_bf16_f32 v64, v64, v65
	v_cvt_pk_bf16_f32 v65, v66, v67
	v_add_f32_e32 v195, v195, v174
	v_add_f32_e32 v195, v195, v176
	v_add_u32_e32 v202, 0x30000, v201
	global_store_dwordx2 v202, v[76:77], s[18:19]
	global_store_dwordx2 v202, v[72:73], s[18:19] offset:32
	global_store_dwordx2 v202, v[68:69], s[18:19] offset:256
	global_store_dwordx2 v202, v[64:65], s[18:19] offset:288
	s_waitcnt vmcnt(28)
	v_lshlrev_b32_e32 v188, 16, v180
	v_and_b32_e32 v189, 0xffff0000, v180
	v_lshlrev_b32_e32 v190, 16, v181
	v_and_b32_e32 v191, 0xffff0000, v181
	v_pk_add_f32 v[60:61], v[60:61], v[188:189]
	v_pk_add_f32 v[62:63], v[62:63], v[190:191]
	v_lshlrev_b32_e32 v188, 16, v182
	v_and_b32_e32 v189, 0xffff0000, v182
	v_lshlrev_b32_e32 v190, 16, v183
	v_and_b32_e32 v191, 0xffff0000, v183
	v_pk_add_f32 v[56:57], v[56:57], v[188:189]
	v_pk_add_f32 v[58:59], v[58:59], v[190:191]
	v_lshlrev_b32_e32 v188, 16, v184
	v_and_b32_e32 v189, 0xffff0000, v184
	v_lshlrev_b32_e32 v190, 16, v185
	v_and_b32_e32 v191, 0xffff0000, v185
	v_pk_add_f32 v[52:53], v[52:53], v[188:189]
	v_pk_add_f32 v[54:55], v[54:55], v[190:191]
	v_lshlrev_b32_e32 v188, 16, v186
	v_and_b32_e32 v189, 0xffff0000, v186
	v_lshlrev_b32_e32 v190, 16, v187
	v_and_b32_e32 v191, 0xffff0000, v187
	v_pk_add_f32 v[48:49], v[48:49], v[188:189]
	v_pk_add_f32 v[50:51], v[50:51], v[190:191]
	v_mul_f32_e32 v180, v61, v61
	v_mul_f32_e32 v182, v57, v57
	v_mul_f32_e32 v184, v53, v53
	v_mul_f32_e32 v186, v49, v49
	v_mul_f32_e32 v181, v63, v63
	v_mul_f32_e32 v183, v59, v59
	v_mul_f32_e32 v185, v55, v55
	v_mul_f32_e32 v187, v51, v51
	v_fmac_f32_e32 v180, v60, v60
	v_fmac_f32_e32 v182, v56, v56
	v_fmac_f32_e32 v184, v52, v52
	v_fmac_f32_e32 v186, v48, v48
	v_fmac_f32_e32 v181, v62, v62
	v_fmac_f32_e32 v183, v58, v58
	v_fmac_f32_e32 v185, v54, v54
	v_fmac_f32_e32 v187, v50, v50
	v_add_f32_e32 v180, v180, v181
	v_add_f32_e32 v182, v182, v183
	v_add_f32_e32 v184, v184, v185
	v_add_f32_e32 v186, v186, v187
	v_add_f32_e32 v196, v180, v182
	v_cvt_pk_bf16_f32 v60, v60, v61
	v_cvt_pk_bf16_f32 v61, v62, v63
	v_cvt_pk_bf16_f32 v56, v56, v57
	v_cvt_pk_bf16_f32 v57, v58, v59
	v_cvt_pk_bf16_f32 v52, v52, v53
	v_cvt_pk_bf16_f32 v53, v54, v55
	v_cvt_pk_bf16_f32 v48, v48, v49
	v_cvt_pk_bf16_f32 v49, v50, v51
	v_add_f32_e32 v196, v196, v184
	v_add_f32_e32 v196, v196, v186
	v_add_u32_e32 v202, 0x80000, v201
	global_store_dwordx2 v202, v[60:61], s[18:19]
	global_store_dwordx2 v202, v[56:57], s[18:19] offset:32
	global_store_dwordx2 v202, v[52:53], s[18:19] offset:256
	global_store_dwordx2 v202, v[48:49], s[18:19] offset:288
	s_waitcnt vmcnt(24)
	v_lshlrev_b32_e32 v188, 16, v140
	v_and_b32_e32 v189, 0xffff0000, v140
	v_lshlrev_b32_e32 v190, 16, v141
	v_and_b32_e32 v191, 0xffff0000, v141
	v_pk_add_f32 v[44:45], v[44:45], v[188:189]
	v_pk_add_f32 v[46:47], v[46:47], v[190:191]
	v_lshlrev_b32_e32 v188, 16, v142
	v_and_b32_e32 v189, 0xffff0000, v142
	v_lshlrev_b32_e32 v190, 16, v143
	v_and_b32_e32 v191, 0xffff0000, v143
	v_pk_add_f32 v[40:41], v[40:41], v[188:189]
	v_pk_add_f32 v[42:43], v[42:43], v[190:191]
	v_lshlrev_b32_e32 v188, 16, v150
	v_and_b32_e32 v189, 0xffff0000, v150
	v_lshlrev_b32_e32 v190, 16, v151
	v_and_b32_e32 v191, 0xffff0000, v151
	v_pk_add_f32 v[36:37], v[36:37], v[188:189]
	v_pk_add_f32 v[38:39], v[38:39], v[190:191]
	v_lshlrev_b32_e32 v188, 16, v152
	v_and_b32_e32 v189, 0xffff0000, v152
	v_lshlrev_b32_e32 v190, 16, v153
	v_and_b32_e32 v191, 0xffff0000, v153
	v_pk_add_f32 v[32:33], v[32:33], v[188:189]
	v_pk_add_f32 v[34:35], v[34:35], v[190:191]
	v_mul_f32_e32 v140, v45, v45
	v_mul_f32_e32 v142, v41, v41
	v_mul_f32_e32 v150, v37, v37
	v_mul_f32_e32 v152, v33, v33
	v_mul_f32_e32 v141, v47, v47
	v_mul_f32_e32 v143, v43, v43
	v_mul_f32_e32 v151, v39, v39
	v_mul_f32_e32 v153, v35, v35
	v_fmac_f32_e32 v140, v44, v44
	v_fmac_f32_e32 v142, v40, v40
	v_fmac_f32_e32 v150, v36, v36
	v_fmac_f32_e32 v152, v32, v32
	v_fmac_f32_e32 v141, v46, v46
	v_fmac_f32_e32 v143, v42, v42
	v_fmac_f32_e32 v151, v38, v38
	v_fmac_f32_e32 v153, v34, v34
	v_add_f32_e32 v140, v140, v141
	v_add_f32_e32 v142, v142, v143
	v_add_f32_e32 v150, v150, v151
	v_add_f32_e32 v152, v152, v153
	v_add_f32_e32 v197, v140, v142
	v_cvt_pk_bf16_f32 v44, v44, v45
	v_cvt_pk_bf16_f32 v45, v46, v47
	v_cvt_pk_bf16_f32 v40, v40, v41
	v_cvt_pk_bf16_f32 v41, v42, v43
	v_cvt_pk_bf16_f32 v36, v36, v37
	v_cvt_pk_bf16_f32 v37, v38, v39
	v_cvt_pk_bf16_f32 v32, v32, v33
	v_cvt_pk_bf16_f32 v33, v34, v35
	v_add_f32_e32 v197, v197, v150
	v_add_f32_e32 v197, v197, v152
	v_add_u32_e32 v202, 0x90000, v201
	global_store_dwordx2 v202, v[44:45], s[18:19]
	global_store_dwordx2 v202, v[40:41], s[18:19] offset:32
	global_store_dwordx2 v202, v[36:37], s[18:19] offset:256
	global_store_dwordx2 v202, v[32:33], s[18:19] offset:288
	s_waitcnt vmcnt(20)
	v_lshlrev_b32_e32 v188, 16, v154
	v_and_b32_e32 v189, 0xffff0000, v154
	v_lshlrev_b32_e32 v190, 16, v155
	v_and_b32_e32 v191, 0xffff0000, v155
	v_pk_add_f32 v[28:29], v[28:29], v[188:189]
	v_pk_add_f32 v[30:31], v[30:31], v[190:191]
	v_lshlrev_b32_e32 v188, 16, v156
	v_and_b32_e32 v189, 0xffff0000, v156
	v_lshlrev_b32_e32 v190, 16, v157
	v_and_b32_e32 v191, 0xffff0000, v157
	v_pk_add_f32 v[24:25], v[24:25], v[188:189]
	v_pk_add_f32 v[26:27], v[26:27], v[190:191]
	v_lshlrev_b32_e32 v188, 16, v158
	v_and_b32_e32 v189, 0xffff0000, v158
	v_lshlrev_b32_e32 v190, 16, v159
	v_and_b32_e32 v191, 0xffff0000, v159
	v_pk_add_f32 v[20:21], v[20:21], v[188:189]
	v_pk_add_f32 v[22:23], v[22:23], v[190:191]
	v_lshlrev_b32_e32 v188, 16, v160
	v_and_b32_e32 v189, 0xffff0000, v160
	v_lshlrev_b32_e32 v190, 16, v161
	v_and_b32_e32 v191, 0xffff0000, v161
	v_pk_add_f32 v[16:17], v[16:17], v[188:189]
	v_pk_add_f32 v[18:19], v[18:19], v[190:191]
	v_mul_f32_e32 v154, v29, v29
	v_mul_f32_e32 v156, v25, v25
	v_mul_f32_e32 v158, v21, v21
	v_mul_f32_e32 v160, v17, v17
	v_mul_f32_e32 v155, v31, v31
	v_mul_f32_e32 v157, v27, v27
	v_mul_f32_e32 v159, v23, v23
	v_mul_f32_e32 v161, v19, v19
	v_fmac_f32_e32 v154, v28, v28
	v_fmac_f32_e32 v156, v24, v24
	v_fmac_f32_e32 v158, v20, v20
	v_fmac_f32_e32 v160, v16, v16
	v_fmac_f32_e32 v155, v30, v30
	v_fmac_f32_e32 v157, v26, v26
	v_fmac_f32_e32 v159, v22, v22
	v_fmac_f32_e32 v161, v18, v18
	v_add_f32_e32 v154, v154, v155
	v_add_f32_e32 v156, v156, v157
	v_add_f32_e32 v158, v158, v159
	v_add_f32_e32 v160, v160, v161
	v_add_f32_e32 v198, v154, v156
	v_cvt_pk_bf16_f32 v28, v28, v29
	v_cvt_pk_bf16_f32 v29, v30, v31
	v_cvt_pk_bf16_f32 v24, v24, v25
	v_cvt_pk_bf16_f32 v25, v26, v27
	v_cvt_pk_bf16_f32 v20, v20, v21
	v_cvt_pk_bf16_f32 v21, v22, v23
	v_cvt_pk_bf16_f32 v16, v16, v17
	v_cvt_pk_bf16_f32 v17, v18, v19
	v_add_f32_e32 v198, v198, v158
	v_add_f32_e32 v198, v198, v160
	v_add_u32_e32 v202, 0xa0000, v201
	global_store_dwordx2 v202, v[28:29], s[18:19]
	global_store_dwordx2 v202, v[24:25], s[18:19] offset:32
	global_store_dwordx2 v202, v[20:21], s[18:19] offset:256
	global_store_dwordx2 v202, v[16:17], s[18:19] offset:288
	s_waitcnt vmcnt(16)
	v_lshlrev_b32_e32 v188, 16, v162
	v_and_b32_e32 v189, 0xffff0000, v162
	v_lshlrev_b32_e32 v190, 16, v163
	v_and_b32_e32 v191, 0xffff0000, v163
	v_pk_add_f32 v[12:13], v[12:13], v[188:189]
	v_pk_add_f32 v[14:15], v[14:15], v[190:191]
	v_lshlrev_b32_e32 v188, 16, v164
	v_and_b32_e32 v189, 0xffff0000, v164
	v_lshlrev_b32_e32 v190, 16, v165
	v_and_b32_e32 v191, 0xffff0000, v165
	v_pk_add_f32 v[8:9], v[8:9], v[188:189]
	v_pk_add_f32 v[10:11], v[10:11], v[190:191]
	v_lshlrev_b32_e32 v188, 16, v166
	v_and_b32_e32 v189, 0xffff0000, v166
	v_lshlrev_b32_e32 v190, 16, v167
	v_and_b32_e32 v191, 0xffff0000, v167
	v_pk_add_f32 v[4:5], v[4:5], v[188:189]
	v_pk_add_f32 v[6:7], v[6:7], v[190:191]
	v_lshlrev_b32_e32 v188, 16, v168
	v_and_b32_e32 v189, 0xffff0000, v168
	v_lshlrev_b32_e32 v190, 16, v169
	v_and_b32_e32 v191, 0xffff0000, v169
	v_pk_add_f32 v[0:1], v[0:1], v[188:189]
	v_pk_add_f32 v[2:3], v[2:3], v[190:191]
	v_mul_f32_e32 v162, v13, v13
	v_mul_f32_e32 v164, v9, v9
	v_mul_f32_e32 v166, v5, v5
	v_mul_f32_e32 v168, v1, v1
	v_mul_f32_e32 v163, v15, v15
	v_mul_f32_e32 v165, v11, v11
	v_mul_f32_e32 v167, v7, v7
	v_mul_f32_e32 v169, v3, v3
	v_fmac_f32_e32 v162, v12, v12
	v_fmac_f32_e32 v164, v8, v8
	v_fmac_f32_e32 v166, v4, v4
	v_fmac_f32_e32 v168, v0, v0
	v_fmac_f32_e32 v163, v14, v14
	v_fmac_f32_e32 v165, v10, v10
	v_fmac_f32_e32 v167, v6, v6
	v_fmac_f32_e32 v169, v2, v2
	v_add_f32_e32 v162, v162, v163
	v_add_f32_e32 v164, v164, v165
	v_add_f32_e32 v166, v166, v167
	v_add_f32_e32 v168, v168, v169
	v_add_f32_e32 v199, v162, v164
	v_cvt_pk_bf16_f32 v12, v12, v13
	v_cvt_pk_bf16_f32 v13, v14, v15
	v_cvt_pk_bf16_f32 v8, v8, v9
	v_cvt_pk_bf16_f32 v9, v10, v11
	v_cvt_pk_bf16_f32 v4, v4, v5
	v_cvt_pk_bf16_f32 v5, v6, v7
	v_cvt_pk_bf16_f32 v0, v0, v1
	v_cvt_pk_bf16_f32 v1, v2, v3
	v_add_f32_e32 v199, v199, v166
	v_add_f32_e32 v199, v199, v168
	v_add_u32_e32 v202, 0xb0000, v201
	global_store_dwordx2 v202, v[12:13], s[18:19]
	global_store_dwordx2 v202, v[8:9], s[18:19] offset:32
	global_store_dwordx2 v202, v[4:5], s[18:19] offset:256
	global_store_dwordx2 v202, v[0:1], s[18:19] offset:288
	ds_bpermute_b32 v140, v205, v192
	ds_bpermute_b32 v141, v205, v193
	ds_bpermute_b32 v142, v205, v194
	ds_bpermute_b32 v143, v205, v195
	ds_bpermute_b32 v150, v205, v196
	ds_bpermute_b32 v151, v205, v197
	ds_bpermute_b32 v152, v205, v198
	ds_bpermute_b32 v153, v205, v199
	s_waitcnt lgkmcnt(0)
	v_add_f32_e32 v192, v192, v140
	v_add_f32_e32 v193, v193, v141
	v_add_f32_e32 v194, v194, v142
	v_add_f32_e32 v195, v195, v143
	v_add_f32_e32 v196, v196, v150
	v_add_f32_e32 v197, v197, v151
	v_add_f32_e32 v198, v198, v152
	v_add_f32_e32 v199, v199, v153
	ds_bpermute_b32 v140, v206, v192
	ds_bpermute_b32 v141, v206, v193
	ds_bpermute_b32 v142, v206, v194
	ds_bpermute_b32 v143, v206, v195
	ds_bpermute_b32 v150, v206, v196
	ds_bpermute_b32 v151, v206, v197
	ds_bpermute_b32 v152, v206, v198
	ds_bpermute_b32 v153, v206, v199
	s_waitcnt lgkmcnt(0)
	v_add_f32_e32 v192, v192, v140
	v_add_f32_e32 v193, v193, v141
	v_add_f32_e32 v194, v194, v142
	v_add_f32_e32 v195, v195, v143
	v_add_f32_e32 v196, v196, v150
	v_add_f32_e32 v197, v197, v151
	v_add_f32_e32 v198, v198, v152
	v_add_f32_e32 v199, v199, v153
	v_cmp_gt_u32_e32 vcc, 16, v204
	s_and_saveexec_b64 s[28:29], vcc
	global_atomic_add_f32 v203, v192, s[0:1]
	global_atomic_add_f32 v203, v193, s[0:1] offset:64
	global_atomic_add_f32 v203, v194, s[0:1] offset:128
	global_atomic_add_f32 v203, v195, s[0:1] offset:192
	global_atomic_add_f32 v203, v196, s[0:1] offset:512
	global_atomic_add_f32 v203, v197, s[0:1] offset:576
	global_atomic_add_f32 v203, v198, s[0:1] offset:640
	global_atomic_add_f32 v203, v199, s[0:1] offset:704
	s_mov_b64 exec, s[28:29]
	s_andn2_b64 vcc, exec, s[6:7]
	s_mov_b64 s[6:7], -1
	s_cbranch_vccnz .LBB0_847
	s_andn2_b64 vcc, exec, s[2:3]
	s_cbranch_vccnz .LBB0_846
	s_barrier
	s_branch .LBB0_846
